# finalize: 8 Yl record loads and 16 direction-0 fragment loads issued together before the unpack (one round trip instead of five)
# speedup vs baseline: 1.0079x; 1.0079x over previous
.LBB0_472:
	s_lshl_b64 s[28:29], s[38:39], 15
	s_waitcnt lgkmcnt(0)
	s_add_u32 s3, s36, s28
	v_ashrrev_i32_e32 v152, 5, v150
	s_addc_u32 s37, s37, s29
	s_lshl_b64 s[28:29], s[30:31], 13
	v_and_b32_e32 v151, 31, v150
	v_lshlrev_b32_e32 v153, 4, v152
	s_add_u32 s38, s68, s28
	s_addc_u32 s39, s69, s29
	v_lshl_add_u32 v130, v151, 5, v153
	s_add_u32 s28, s3, 0x6000
	v_add_u32_e32 v2, 0xc00, v130
	s_addc_u32 s29, s37, 0
	v_ashrrev_i32_e32 v3, 31, v2
	v_lshl_add_u64 v[6:7], v[2:3], 1, s[28:29]
	global_load_dwordx4 v[2:5], v[6:7], off offset:16 nt
	s_nop 0
	global_load_dwordx4 v[6:9], v[6:7], off nt
	v_ashrrev_i32_e32 v131, 31, v130
	v_lshlrev_b64 v[132:133], 1, v[130:131]
	v_lshl_add_u64 v[54:55], s[28:29], 0, v[132:133]
	v_add_u32_e32 v18, 0x400, v130
	v_ashrrev_i32_e32 v19, 31, v18
	v_lshl_add_u64 v[22:23], v[18:19], 1, s[28:29]
	v_add_u32_e32 v34, 0x800, v130
	v_ashrrev_i32_e32 v35, 31, v34
	v_lshl_add_u64 v[38:39], v[34:35], 1, s[28:29]
	global_load_dwordx4 v[18:21], v[22:23], off offset:16 nt
	s_nop 0
	global_load_dwordx4 v[22:25], v[22:23], off nt
	s_nop 0
	global_load_dwordx4 v[34:37], v[38:39], off offset:16 nt
	s_nop 0
	global_load_dwordx4 v[38:41], v[38:39], off nt
	s_nop 0
	global_load_dwordx4 v[50:53], v[54:55], off offset:16 nt
	s_nop 0
	global_load_dwordx4 v[54:57], v[54:55], off nt
	v_lshlrev_b32_e32 v134, 3, v150
	s_add_u32 s36, s3, 0x2000
	v_lshl_add_u64 v[94:95], s[38:39], 0, v[132:133]
	v_add_u32_e32 v136, 0x200, v134
	v_add_u32_e32 v138, 0x400, v134
	v_add_u32_e32 v140, 0x600, v134
	s_movk_i32 s3, 0x1000
	v_add_u32_e32 v142, 0x800, v134
	s_addc_u32 s37, s37, 0
	v_ashrrev_i32_e32 v135, 31, v134
	v_ashrrev_i32_e32 v137, 31, v136
	v_ashrrev_i32_e32 v139, 31, v138
	v_ashrrev_i32_e32 v141, 31, v140
	v_add_co_u32_e32 v106, vcc, s3, v94
	v_ashrrev_i32_e32 v143, 31, v142
	v_add_u32_e32 v144, 0xa00, v134
	v_lshl_add_u64 v[74:75], v[134:135], 1, s[36:37]
	v_lshl_add_u64 v[78:79], v[136:137], 1, s[36:37]
	v_lshl_add_u64 v[90:91], v[138:139], 1, s[36:37]
	v_lshl_add_u64 v[96:97], v[140:141], 1, s[36:37]
	v_addc_co_u32_e32 v107, vcc, 0, v95, vcc
	v_lshl_add_u64 v[108:109], v[142:143], 1, s[36:37]
	v_ashrrev_i32_e32 v145, 31, v144
	v_add_u32_e32 v146, 0xc00, v134
	v_add_u32_e32 v148, 0xe00, v134
	v_ashrrev_i32_e32 v147, 31, v146
	v_ashrrev_i32_e32 v149, 31, v148
	v_lshl_add_u64 v[122:123], v[146:147], 1, s[36:37]
	v_lshl_add_u64 v[126:127], v[148:149], 1, s[36:37]
	global_load_dwordx4 v[70:73], v[94:95], off nt
	global_load_dwordx4 v[66:69], v[94:95], off offset:2048 nt
	s_nop 0
	global_load_dwordx4 v[74:77], v[74:75], off nt
	s_nop 0
	global_load_dwordx4 v[86:89], v[78:79], off nt
	global_load_dwordx4 v[82:85], v[94:95], off offset:16 nt
	s_nop 0
	global_load_dwordx4 v[78:81], v[94:95], off offset:2064 nt
	global_load_dwordx4 v[102:105], v[96:97], off nt
	s_nop 0
	global_load_dwordx4 v[90:93], v[90:91], off nt
	s_nop 0
	global_load_dwordx4 v[98:101], v[106:107], off nt
	global_load_dwordx4 v[94:97], v[106:107], off offset:2048 nt
	global_load_dwordx4 v[110:113], v[108:109], off nt
	v_lshl_add_u64 v[108:109], v[144:145], 1, s[36:37]
	global_load_dwordx4 v[118:121], v[108:109], off nt
	global_load_dwordx4 v[114:117], v[106:107], off offset:16 nt
	s_nop 0
	global_load_dwordx4 v[106:109], v[106:107], off offset:2064 nt
	s_nop 0
	global_load_dwordx4 v[122:125], v[122:123], off nt
	s_nop 0
	global_load_dwordx4 v[126:129], v[126:127], off nt
	s_waitcnt vmcnt(23)
	v_cvt_f32_f16_e32 v10, v2
	s_waitcnt vmcnt(22)
	v_cvt_f32_f16_e32 v228, v6
	v_cvt_f32_f16_sdwa v229, v6 dst_sel:DWORD dst_unused:UNUSED_PAD src0_sel:WORD_1
	v_cvt_f32_f16_sdwa v11, v2 dst_sel:DWORD dst_unused:UNUSED_PAD src0_sel:WORD_1
	v_cvt_f32_f16_e32 v2, v3
	v_cvt_f32_f16_sdwa v3, v3 dst_sel:DWORD dst_unused:UNUSED_PAD src0_sel:WORD_1
	v_cvt_f32_f16_e32 v12, v4
	v_cvt_f32_f16_sdwa v13, v4 dst_sel:DWORD dst_unused:UNUSED_PAD src0_sel:WORD_1
	v_cvt_f32_f16_e32 v230, v7
	v_cvt_f32_f16_sdwa v231, v7 dst_sel:DWORD dst_unused:UNUSED_PAD src0_sel:WORD_1
	v_cvt_f32_f16_e32 v4, v5
	v_cvt_f32_f16_sdwa v5, v5 dst_sel:DWORD dst_unused:UNUSED_PAD src0_sel:WORD_1
	v_pk_add_f32 v[14:15], v[12:13], 0 op_sel_hi:[1,0]
	v_pk_add_f32 v[12:13], v[2:3], 0 op_sel_hi:[1,0]
	v_pk_add_f32 v[2:3], v[228:229], 0 op_sel_hi:[1,0]
	v_pk_add_f32 v[16:17], v[4:5], 0 op_sel_hi:[1,0]
	v_pk_add_f32 v[4:5], v[230:231], 0 op_sel_hi:[1,0]
	v_cvt_f32_f16_e32 v6, v8
	v_cvt_f32_f16_sdwa v7, v8 dst_sel:DWORD dst_unused:UNUSED_PAD src0_sel:WORD_1
	v_cvt_f32_f16_e32 v8, v9
	v_cvt_f32_f16_sdwa v9, v9 dst_sel:DWORD dst_unused:UNUSED_PAD src0_sel:WORD_1
	v_pk_add_f32 v[10:11], v[10:11], 0 op_sel_hi:[1,0]
	v_pk_add_f32 v[6:7], v[6:7], 0 op_sel_hi:[1,0]
	v_pk_add_f32 v[8:9], v[8:9], 0 op_sel_hi:[1,0]
	s_waitcnt vmcnt(21)
	v_cvt_f32_f16_e32 v26, v18
	s_waitcnt vmcnt(20)
	v_cvt_f32_f16_e32 v232, v22
	v_cvt_f32_f16_sdwa v233, v22 dst_sel:DWORD dst_unused:UNUSED_PAD src0_sel:WORD_1
	v_cvt_f32_f16_sdwa v27, v18 dst_sel:DWORD dst_unused:UNUSED_PAD src0_sel:WORD_1
	v_cvt_f32_f16_e32 v18, v19
	v_cvt_f32_f16_sdwa v19, v19 dst_sel:DWORD dst_unused:UNUSED_PAD src0_sel:WORD_1
	v_cvt_f32_f16_e32 v28, v20
	v_cvt_f32_f16_sdwa v29, v20 dst_sel:DWORD dst_unused:UNUSED_PAD src0_sel:WORD_1
	v_cvt_f32_f16_e32 v234, v23
	v_cvt_f32_f16_sdwa v235, v23 dst_sel:DWORD dst_unused:UNUSED_PAD src0_sel:WORD_1
	v_cvt_f32_f16_e32 v20, v21
	v_cvt_f32_f16_sdwa v21, v21 dst_sel:DWORD dst_unused:UNUSED_PAD src0_sel:WORD_1
	v_pk_add_f32 v[30:31], v[28:29], 0 op_sel_hi:[1,0]
	v_pk_add_f32 v[28:29], v[18:19], 0 op_sel_hi:[1,0]
	v_pk_add_f32 v[18:19], v[232:233], 0 op_sel_hi:[1,0]
	v_pk_add_f32 v[32:33], v[20:21], 0 op_sel_hi:[1,0]
	v_pk_add_f32 v[20:21], v[234:235], 0 op_sel_hi:[1,0]
	v_cvt_f32_f16_e32 v22, v24
	v_cvt_f32_f16_sdwa v23, v24 dst_sel:DWORD dst_unused:UNUSED_PAD src0_sel:WORD_1
	v_cvt_f32_f16_e32 v24, v25
	v_cvt_f32_f16_sdwa v25, v25 dst_sel:DWORD dst_unused:UNUSED_PAD src0_sel:WORD_1
	v_pk_add_f32 v[26:27], v[26:27], 0 op_sel_hi:[1,0]
	v_pk_add_f32 v[22:23], v[22:23], 0 op_sel_hi:[1,0]
	v_pk_add_f32 v[24:25], v[24:25], 0 op_sel_hi:[1,0]
	s_waitcnt vmcnt(19)
	v_cvt_f32_f16_e32 v42, v34
	s_waitcnt vmcnt(18)
	v_cvt_f32_f16_e32 v236, v38
	v_cvt_f32_f16_sdwa v237, v38 dst_sel:DWORD dst_unused:UNUSED_PAD src0_sel:WORD_1
	v_cvt_f32_f16_e32 v238, v39
	v_cvt_f32_f16_sdwa v239, v39 dst_sel:DWORD dst_unused:UNUSED_PAD src0_sel:WORD_1
	v_cvt_f32_f16_sdwa v43, v34 dst_sel:DWORD dst_unused:UNUSED_PAD src0_sel:WORD_1
	v_cvt_f32_f16_e32 v34, v35
	v_cvt_f32_f16_sdwa v35, v35 dst_sel:DWORD dst_unused:UNUSED_PAD src0_sel:WORD_1
	v_cvt_f32_f16_e32 v44, v36
	v_cvt_f32_f16_sdwa v45, v36 dst_sel:DWORD dst_unused:UNUSED_PAD src0_sel:WORD_1
	v_cvt_f32_f16_e32 v36, v37
	v_cvt_f32_f16_sdwa v37, v37 dst_sel:DWORD dst_unused:UNUSED_PAD src0_sel:WORD_1
	v_cvt_f32_f16_e32 v38, v40
	v_pk_add_f32 v[46:47], v[44:45], 0 op_sel_hi:[1,0]
	v_pk_add_f32 v[44:45], v[34:35], 0 op_sel_hi:[1,0]
	v_pk_add_f32 v[48:49], v[36:37], 0 op_sel_hi:[1,0]
	v_pk_add_f32 v[36:37], v[238:239], 0 op_sel_hi:[1,0]
	v_pk_add_f32 v[34:35], v[236:237], 0 op_sel_hi:[1,0]
	v_cvt_f32_f16_sdwa v39, v40 dst_sel:DWORD dst_unused:UNUSED_PAD src0_sel:WORD_1
	v_cvt_f32_f16_e32 v40, v41
	v_cvt_f32_f16_sdwa v41, v41 dst_sel:DWORD dst_unused:UNUSED_PAD src0_sel:WORD_1
	v_pk_add_f32 v[42:43], v[42:43], 0 op_sel_hi:[1,0]
	v_pk_add_f32 v[38:39], v[38:39], 0 op_sel_hi:[1,0]
	v_pk_add_f32 v[40:41], v[40:41], 0 op_sel_hi:[1,0]
	s_waitcnt vmcnt(17)
	v_cvt_f32_f16_e32 v58, v50
	s_waitcnt vmcnt(16)
	v_cvt_f32_f16_e32 v240, v54
	v_cvt_f32_f16_sdwa v241, v54 dst_sel:DWORD dst_unused:UNUSED_PAD src0_sel:WORD_1
	v_cvt_f32_f16_e32 v242, v55
	v_cvt_f32_f16_sdwa v243, v55 dst_sel:DWORD dst_unused:UNUSED_PAD src0_sel:WORD_1
	v_cvt_f32_f16_sdwa v59, v50 dst_sel:DWORD dst_unused:UNUSED_PAD src0_sel:WORD_1
	v_cvt_f32_f16_e32 v50, v51
	v_cvt_f32_f16_sdwa v51, v51 dst_sel:DWORD dst_unused:UNUSED_PAD src0_sel:WORD_1
	v_cvt_f32_f16_e32 v60, v52
	v_cvt_f32_f16_sdwa v61, v52 dst_sel:DWORD dst_unused:UNUSED_PAD src0_sel:WORD_1
	v_cvt_f32_f16_e32 v52, v53
	v_cvt_f32_f16_sdwa v53, v53 dst_sel:DWORD dst_unused:UNUSED_PAD src0_sel:WORD_1
	v_cvt_f32_f16_e32 v54, v56
	v_pk_add_f32 v[62:63], v[60:61], 0 op_sel_hi:[1,0]
	v_pk_add_f32 v[60:61], v[50:51], 0 op_sel_hi:[1,0]
	v_pk_add_f32 v[64:65], v[52:53], 0 op_sel_hi:[1,0]
	v_pk_add_f32 v[52:53], v[242:243], 0 op_sel_hi:[1,0]
	v_pk_add_f32 v[50:51], v[240:241], 0 op_sel_hi:[1,0]
	v_cvt_f32_f16_sdwa v55, v56 dst_sel:DWORD dst_unused:UNUSED_PAD src0_sel:WORD_1
	v_cvt_f32_f16_e32 v56, v57
	v_cvt_f32_f16_sdwa v57, v57 dst_sel:DWORD dst_unused:UNUSED_PAD src0_sel:WORD_1
	v_pk_add_f32 v[58:59], v[58:59], 0 op_sel_hi:[1,0]
	v_pk_add_f32 v[56:57], v[56:57], 0 op_sel_hi:[1,0]
	v_pk_add_f32 v[54:55], v[54:55], 0 op_sel_hi:[1,0]
	s_waitcnt vmcnt(13)
	s_nop 0
	v_mfma_f32_32x32x16_f16 v[50:65], v[70:73], v[74:77], v[50:65]
	s_xor_b32 s30, s30, 0x7f
	s_ashr_i32 s31, s30, 31
	s_cmpk_lt_i32 s30, 0x800
	s_mov_b64 s[38:39], s[30:31]
	s_mov_b64 s[36:37], s[26:27]
	v_mfma_f32_32x32x16_f16 v[34:49], v[66:69], v[74:77], v[34:49]
	s_waitcnt vmcnt(12)
	v_mfma_f32_32x32x16_f16 v[18:33], v[70:73], v[86:89], v[18:33]
	v_mfma_f32_32x32x16_f16 v[2:17], v[66:69], v[86:89], v[2:17]
	s_waitcnt vmcnt(8)
	v_mfma_f32_32x32x16_f16 v[50:65], v[82:85], v[90:93], v[50:65]
	v_mfma_f32_32x32x16_f16 v[34:49], v[78:81], v[90:93], v[34:49]
	v_mfma_f32_32x32x16_f16 v[18:33], v[82:85], v[102:105], v[18:33]
	v_mfma_f32_32x32x16_f16 v[2:17], v[78:81], v[102:105], v[2:17]
	s_waitcnt vmcnt(5)
	v_mfma_f32_32x32x16_f16 v[50:65], v[98:101], v[110:113], v[50:65]
	v_mfma_f32_32x32x16_f16 v[34:49], v[94:97], v[110:113], v[34:49]
	s_waitcnt vmcnt(4)
	v_mfma_f32_32x32x16_f16 v[18:33], v[98:101], v[118:121], v[18:33]
	v_mfma_f32_32x32x16_f16 v[2:17], v[94:97], v[118:121], v[2:17]
	s_waitcnt vmcnt(1)
	v_mfma_f32_32x32x16_f16 v[50:65], v[114:117], v[122:125], v[50:65]
	v_mfma_f32_32x32x16_f16 v[34:49], v[106:109], v[122:125], v[34:49]
	s_waitcnt vmcnt(0)
	v_mfma_f32_32x32x16_f16 v[18:33], v[114:117], v[126:129], v[18:33]
	v_mfma_f32_32x32x16_f16 v[2:17], v[106:109], v[126:129], v[2:17]
	s_cbranch_scc1 .LBB0_451
	v_readlane_b32 s28, v254, 59
	v_readlane_b32 s29, v254, 60
	s_load_dwordx2 s[36:37], s[28:29], 0xa8
	s_add_i32 s50, s30, 0xfffff800
	s_mov_b64 s[38:39], s[50:51]
	s_branch .LBB0_451
